# v29 with the pass-B ring wait recounted for the widened stores (vmcnt 35 instead of 63)
# baseline (speedup 1.0000x reference)
; #define LAS __attribute__((address_space(3)))
; __device__ __forceinline__ unsigned cvtpk_s(float lo, float hi) { f32x2_t v = {lo, hi}; bf16x2_t b = __builtin_convertvector(v, bf16x2_t); return __builtin_bit_cast(unsigned, b); }
; template <bool FULL>
; __device__ __forceinline__ void s5_pass(const Params& P, LAS unsigned char* lds, int bx, int tid_in) {
;     ...
;         for (int t0 = 0; t0 < S5_SEGLEN; t0 += 16) {
;             const bf16x8 ca = ua; bf16x8 cb0, cb1; if (FULL) { cb0 = ub0; cb1 = ub1; }
;             if (t0 + 16 < S5_SEGLEN) { const size_t o = (size_t)(t0 + 16) * BR; ua = *(const bf16x8*)(u32p + o); if (FULL) { ub0 = *(const bf16x8*)(u16p + o); ub1 = *(const bf16x8*)(u16p + o + (size_t)4 * SEQ * BR); } }
;             if (FULL && kg >= 2) { cb0 = (bf16x8){0, 0, 0, 0, 0, 0, 0, 0}; cb1 = cb0; }
;             f32x16 acc[4];
; #pragma unroll
;             for (int j = 0; j < 4; ++j) {
; #pragma unroll
;                 for (int r = 0; r < 16; ++r) acc[j][r] = 0.f;
;                 acc[j] = __builtin_amdgcn_mfma_f32_32x32x16_bf16(ca, bfr[j], acc[j], 0, 0, 0); }
; #pragma unroll
;             for (int r = 0; r < 16; ++r) {
;                 const float n0r = ar0 * h0r - ai0 * h0i + acc[0][r], n0i = ar0 * h0i + ai0 * h0r + acc[2][r];
;                 const float n1r = ar1 * h1r - ai1 * h1i + acc[1][r], n1i = ar1 * h1i + ai1 * h1r + acc[3][r];
;                 h0r = n0r; h0i = n0i; h1r = n1r; h1i = n1i;
;                 if (FULL) { *(LAS unsigned*)(hl + (16 * hi + r) * HROW + r32 * 4) = cvtpk_s(n0r, n0i);
;                     *(LAS unsigned*)(hl + (16 * hi + r) * HROW + (32 + r32) * 4) = cvtpk_s(n1r, n1i); }
;             }
.Ls5b_step:
	v_mfma_f32_32x32x16_bf16 v[0:15], v[104:107], v[64:67], 0
	v_mfma_f32_32x32x16_bf16 v[16:31], v[104:107], v[80:83], 0
	v_mfma_f32_32x32x16_bf16 v[32:47], v[104:107], v[68:71], 0
	v_mfma_f32_32x32x16_bf16 v[48:63], v[104:107], v[84:87], 0
	s_cmp_lt_u32 s74, 31
	s_cselect_b32 s76, 0x10000, 0
	s_cmp_lt_u32 s74, 32
	s_cselect_b32 m0, s72, s73
	s_add_i32 s74, s74, 1
	v_add_u32_e32 v186, s72, v184
	v_add_u32_e32 v187, s72, v185
	s_add_i32 s72, s72, 1024
	s_cmp_eq_u32 s72, s73
	s_cselect_b32 s72, s71, s72
	v_cndmask_b32_e64 v187, v187, v214, s[4:5]
	v_fmac_f32_e32 v0, v150, v156
	v_fmac_f32_e32 v16, v150, v157
	v_fmac_f32_e32 v32, v152, v158
	v_fmac_f32_e32 v48, v152, v159
	v_fmac_f32_e32 v0, v154, v157
	v_fmac_f32_e32 v16, v151, v156
	v_fmac_f32_e32 v32, v155, v159
	v_fmac_f32_e32 v48, v153, v158
	v_fmac_f32_e32 v1, v150, v0
	v_fmac_f32_e32 v17, v150, v16
	v_fmac_f32_e32 v33, v152, v32
	v_fmac_f32_e32 v49, v152, v48
	v_fmac_f32_e32 v1, v154, v16
	v_fmac_f32_e32 v17, v151, v0
	v_fmac_f32_e32 v33, v155, v48
	v_fmac_f32_e32 v49, v153, v32
	v_cvt_pk_bf16_f32 v160, v0, v16
	v_cvt_pk_bf16_f32 v161, v32, v48
	ds_write2_b32 v174, v160, v161 offset0:0 offset1:32
	s_waitcnt vmcnt(35)
	ds_read_b128 v[104:107], v186
	v_fmac_f32_e32 v2, v150, v1
	v_fmac_f32_e32 v18, v150, v17
	v_fmac_f32_e32 v34, v152, v33
	v_fmac_f32_e32 v50, v152, v49
	v_fmac_f32_e32 v2, v154, v17
	v_fmac_f32_e32 v18, v151, v1
	v_fmac_f32_e32 v34, v155, v49
	v_fmac_f32_e32 v50, v153, v33
	v_cvt_pk_bf16_f32 v162, v1, v17
	v_cvt_pk_bf16_f32 v163, v33, v49
	ds_write2_b32 v174, v162, v163 offset0:68 offset1:100
	v_fmac_f32_e32 v3, v150, v2
	v_fmac_f32_e32 v19, v150, v18
	v_fmac_f32_e32 v35, v152, v34
	v_fmac_f32_e32 v51, v152, v50
	v_fmac_f32_e32 v3, v154, v18
	v_fmac_f32_e32 v19, v151, v2
	v_fmac_f32_e32 v35, v155, v50
	v_fmac_f32_e32 v51, v153, v34
	v_cvt_pk_bf16_f32 v160, v2, v18
	v_cvt_pk_bf16_f32 v161, v34, v50
	ds_write2_b32 v174, v160, v161 offset0:136 offset1:168
	v_fmac_f32_e32 v4, v150, v3
	v_fmac_f32_e32 v20, v150, v19
	v_fmac_f32_e32 v36, v152, v35
	v_fmac_f32_e32 v52, v152, v51
	v_fmac_f32_e32 v4, v154, v19
	v_fmac_f32_e32 v20, v151, v3
	v_fmac_f32_e32 v36, v155, v51
	v_fmac_f32_e32 v52, v153, v35
	v_cvt_pk_bf16_f32 v162, v3, v19
	v_cvt_pk_bf16_f32 v163, v35, v51
	ds_write2_b32 v174, v162, v163 offset0:204 offset1:236
	v_fmac_f32_e32 v5, v150, v4
	v_fmac_f32_e32 v21, v150, v20
	v_fmac_f32_e32 v37, v152, v36
	v_fmac_f32_e32 v53, v152, v52
	v_fmac_f32_e32 v5, v154, v20
	v_fmac_f32_e32 v21, v151, v4
	v_fmac_f32_e32 v37, v155, v52
	v_fmac_f32_e32 v53, v153, v36
	v_cvt_pk_bf16_f32 v160, v4, v20
	v_cvt_pk_bf16_f32 v161, v36, v52
	ds_write2_b32 v226, v160, v161 offset0:16 offset1:48
	v_fmac_f32_e32 v6, v150, v5
	v_fmac_f32_e32 v22, v150, v21
	v_fmac_f32_e32 v38, v152, v37
	v_fmac_f32_e32 v54, v152, v53
	v_fmac_f32_e32 v6, v154, v21
	v_fmac_f32_e32 v22, v151, v5
	v_fmac_f32_e32 v38, v155, v53
	v_fmac_f32_e32 v54, v153, v37
	v_cvt_pk_bf16_f32 v162, v5, v21
	v_cvt_pk_bf16_f32 v163, v37, v53
	ds_write2_b32 v226, v162, v163 offset0:84 offset1:116
	v_fmac_f32_e32 v7, v150, v6
	v_fmac_f32_e32 v23, v150, v22
	v_fmac_f32_e32 v39, v152, v38
	v_fmac_f32_e32 v55, v152, v54
	v_fmac_f32_e32 v7, v154, v22
	v_fmac_f32_e32 v23, v151, v6
	v_fmac_f32_e32 v39, v155, v54
	v_fmac_f32_e32 v55, v153, v38
	v_cvt_pk_bf16_f32 v160, v6, v22
	v_cvt_pk_bf16_f32 v161, v38, v54
	ds_write2_b32 v226, v160, v161 offset0:152 offset1:184
	v_fmac_f32_e32 v8, v150, v7
	v_fmac_f32_e32 v24, v150, v23
	v_fmac_f32_e32 v40, v152, v39
	v_fmac_f32_e32 v56, v152, v55
	v_fmac_f32_e32 v8, v154, v23
	v_fmac_f32_e32 v24, v151, v7
	v_fmac_f32_e32 v40, v155, v55
	v_fmac_f32_e32 v56, v153, v39
	v_cvt_pk_bf16_f32 v162, v7, v23
	v_cvt_pk_bf16_f32 v163, v39, v55
	ds_write2_b32 v226, v162, v163 offset0:220 offset1:252
	v_fmac_f32_e32 v9, v150, v8
	v_fmac_f32_e32 v25, v150, v24
	v_fmac_f32_e32 v41, v152, v40
	v_fmac_f32_e32 v57, v152, v56
	v_fmac_f32_e32 v9, v154, v24
	v_fmac_f32_e32 v25, v151, v8
	v_fmac_f32_e32 v41, v155, v56
	v_fmac_f32_e32 v57, v153, v40
	v_cvt_pk_bf16_f32 v160, v8, v24
	v_cvt_pk_bf16_f32 v161, v40, v56
	ds_write2_b32 v227, v160, v161 offset0:32 offset1:64
	v_fmac_f32_e32 v10, v150, v9
	v_fmac_f32_e32 v26, v150, v25
	v_fmac_f32_e32 v42, v152, v41
	v_fmac_f32_e32 v58, v152, v57
	v_fmac_f32_e32 v10, v154, v25
	v_fmac_f32_e32 v26, v151, v9
	v_fmac_f32_e32 v42, v155, v57
	v_fmac_f32_e32 v58, v153, v41
	v_cvt_pk_bf16_f32 v162, v9, v25
	v_cvt_pk_bf16_f32 v163, v41, v57
	ds_write2_b32 v227, v162, v163 offset0:100 offset1:132
	v_fmac_f32_e32 v11, v150, v10
	v_fmac_f32_e32 v27, v150, v26
	v_fmac_f32_e32 v43, v152, v42
	v_fmac_f32_e32 v59, v152, v58
	v_fmac_f32_e32 v11, v154, v26
	v_fmac_f32_e32 v27, v151, v10
	v_fmac_f32_e32 v43, v155, v58
	v_fmac_f32_e32 v59, v153, v42
	v_cvt_pk_bf16_f32 v160, v10, v26
	v_cvt_pk_bf16_f32 v161, v42, v58
	ds_write2_b32 v228, v160, v161 offset0:40 offset1:72
	v_fmac_f32_e32 v12, v150, v11
	v_fmac_f32_e32 v28, v150, v27
	v_fmac_f32_e32 v44, v152, v43
	v_fmac_f32_e32 v60, v152, v59
	v_fmac_f32_e32 v12, v154, v27
	v_fmac_f32_e32 v28, v151, v11
	v_fmac_f32_e32 v44, v155, v59
	v_fmac_f32_e32 v60, v153, v43
	v_cvt_pk_bf16_f32 v162, v11, v27
	v_cvt_pk_bf16_f32 v163, v43, v59
	ds_write2_b32 v228, v162, v163 offset0:108 offset1:140
	v_fmac_f32_e32 v13, v150, v12
	v_fmac_f32_e32 v29, v150, v28
	v_fmac_f32_e32 v45, v152, v44
	v_fmac_f32_e32 v61, v152, v60
	v_fmac_f32_e32 v13, v154, v28
	v_fmac_f32_e32 v29, v151, v12
	v_fmac_f32_e32 v45, v155, v60
	v_fmac_f32_e32 v61, v153, v44
	v_cvt_pk_bf16_f32 v160, v12, v28
	v_cvt_pk_bf16_f32 v161, v44, v60
	ds_write2_b32 v229, v160, v161 offset0:48 offset1:80
	v_fmac_f32_e32 v14, v150, v13
	v_fmac_f32_e32 v30, v150, v29
	v_fmac_f32_e32 v46, v152, v45
	v_fmac_f32_e32 v62, v152, v61
	v_fmac_f32_e32 v14, v154, v29
	v_fmac_f32_e32 v30, v151, v13
	v_fmac_f32_e32 v46, v155, v61
	v_fmac_f32_e32 v62, v153, v45
	v_cvt_pk_bf16_f32 v162, v13, v29
	v_cvt_pk_bf16_f32 v163, v45, v61
	ds_write2_b32 v229, v162, v163 offset0:116 offset1:148
	v_fmac_f32_e32 v15, v150, v14
	v_fmac_f32_e32 v31, v150, v30
	v_fmac_f32_e32 v47, v152, v46
	v_fmac_f32_e32 v63, v152, v62
	v_fmac_f32_e32 v15, v154, v30
	v_fmac_f32_e32 v31, v151, v14
	v_fmac_f32_e32 v47, v155, v62
	v_fmac_f32_e32 v63, v153, v46
	v_cvt_pk_bf16_f32 v160, v14, v30
	v_cvt_pk_bf16_f32 v161, v46, v62
	ds_write2_b32 v230, v160, v161 offset0:56 offset1:88
	v_cvt_pk_bf16_f32 v162, v15, v31
	v_cvt_pk_bf16_f32 v163, v47, v63
	ds_write2_b32 v230, v162, v163 offset0:124 offset1:156
	ds_read_b128 v[116:119], v175
	ds_read_b128 v[120:123], v175 offset:64
	ds_read_b128 v[176:179], v175 offset:128
	ds_read_b128 v[180:183], v175 offset:192
	ds_read_b128 v[190:193], v175 offset:4352
	ds_read_b128 v[194:197], v175 offset:4416
	ds_read_b128 v[198:201], v175 offset:4480
	ds_read_b128 v[202:205], v175 offset:4544
	v_mov_b32_e32 v156, v15
	v_mov_b32_e32 v157, v31
	v_mov_b32_e32 v158, v47
	v_mov_b32_e32 v159, v63
	s_waitcnt lgkmcnt(7)
; #define LAS __attribute__((address_space(3)))
; __device__ __forceinline__ float gelu_tanh(float y) { const float t = (-1.5957691216057308f * LOG2E) * (y + 0.044715f * y * y * y); return y * __builtin_amdgcn_rcpf(1.f + __builtin_amdgcn_exp2f(t)); }
; __device__ __forceinline__ unsigned cvtpk_s(float lo, float hi) { f32x2_t v = {lo, hi}; bf16x2_t b = __builtin_convertvector(v, bf16x2_t); return __builtin_bit_cast(unsigned, b); }
; template <bool FULL>
; __device__ __forceinline__ void s5_pass(const Params& P, LAS unsigned char* lds, int bx, int tid_in) {
;     ...
;             if (FULL) {
; #pragma unroll
;             for (int blk = 0; blk < 2; ++blk) {
;                 f32x4 y = (f32x4){0.f, 0.f, 0.f, 0.f};
; #pragma unroll
;                 for (int kk = 0; kk < 4; ++kk) { const bf16x8 hf = *(const LAS bf16x8*)(hl + (16 * blk + l16) * HROW + kk * 64 + kg * 16);
;                     y = __builtin_amdgcn_mfma_f32_16x16x32_bf16(hf, cfr[kk], y, 0, 0, 0); }
;                 y = __builtin_amdgcn_mfma_f32_16x16x32_bf16(blk ? cb1 : cb0, dh, y, 0, 0, 0);
;                 y = __builtin_amdgcn_mfma_f32_16x16x32_bf16(blk ? cb1 : cb0, dl, y, 0, 0, 0);
;                 bf16_t* o = yp + ((size_t)(4 * blk) * SEQ + t0) * BR;
;                 const unsigned w01 = cvtpk_s(gelu_tanh(y[0]), gelu_tanh(y[1])), w23 = cvtpk_s(gelu_tanh(y[2]), gelu_tanh(y[3]));
;                 o[0] = (bf16_t)(w01 & 0xffffu); o[(size_t)BR] = (bf16_t)(w01 >> 16); o[(size_t)2 * BR] = (bf16_t)(w23 & 0xffffu); o[(size_t)3 * BR] = (bf16_t)(w23 >> 16);
;             }
	v_mfma_f32_16x16x32_bf16 v[206:209], v[116:119], v[72:75], 0
	s_waitcnt lgkmcnt(6)
	v_mfma_f32_16x16x32_bf16 v[206:209], v[120:123], v[76:79], v[206:209]
	s_waitcnt lgkmcnt(5)
	v_mfma_f32_16x16x32_bf16 v[206:209], v[176:179], v[88:91], v[206:209]
	s_waitcnt lgkmcnt(4)
	v_mfma_f32_16x16x32_bf16 v[206:209], v[180:183], v[92:95], v[206:209]
	v_mfma_f32_16x16x32_bf16 v[206:209], v[108:111], v[96:99], v[206:209]
	v_mfma_f32_16x16x32_bf16 v[206:209], v[108:111], v[100:103], v[206:209]
	s_waitcnt lgkmcnt(3)
	v_mfma_f32_16x16x32_bf16 v[210:213], v[190:193], v[72:75], 0
	s_waitcnt lgkmcnt(2)
	v_mfma_f32_16x16x32_bf16 v[210:213], v[194:197], v[76:79], v[210:213]
	s_waitcnt lgkmcnt(1)
	v_mfma_f32_16x16x32_bf16 v[210:213], v[198:201], v[88:91], v[210:213]
	s_waitcnt lgkmcnt(0)
	v_mfma_f32_16x16x32_bf16 v[210:213], v[202:205], v[92:95], v[210:213]
	v_mfma_f32_16x16x32_bf16 v[210:213], v[112:115], v[96:99], v[210:213]
	v_mfma_f32_16x16x32_bf16 v[210:213], v[112:115], v[100:103], v[210:213]
	s_nop 1
	v_mul_f32_e32 v216, 0x3d372713, v206
	v_mul_f32_e32 v217, 0x3d372713, v207
	v_mul_f32_e32 v218, 0x3d372713, v208
	v_mul_f32_e32 v219, 0x3d372713, v209
	v_mul_f32_e32 v216, v206, v216
	v_mul_f32_e32 v217, v207, v217
	v_mul_f32_e32 v218, v208, v218
	v_mul_f32_e32 v219, v209, v219
	v_fma_f32 v216, v206, v216, v206
	v_fma_f32 v217, v207, v217, v207
	v_fma_f32 v218, v208, v218, v208
	v_fma_f32 v219, v209, v219, v209
	v_mul_f32_e32 v216, 0xc0135761, v216
	v_mul_f32_e32 v217, 0xc0135761, v217
	v_mul_f32_e32 v218, 0xc0135761, v218
	v_mul_f32_e32 v219, 0xc0135761, v219
	v_exp_f32_e32 v216, v216
	v_exp_f32_e32 v217, v217
	v_exp_f32_e32 v218, v218
	v_exp_f32_e32 v219, v219
	v_add_f32_e32 v216, 1.0, v216
	v_add_f32_e32 v217, 1.0, v217
	v_add_f32_e32 v218, 1.0, v218
	v_add_f32_e32 v219, 1.0, v219
	v_rcp_f32_e32 v216, v216
	v_rcp_f32_e32 v217, v217
	v_rcp_f32_e32 v218, v218
	v_rcp_f32_e32 v219, v219
	v_mul_f32_e32 v216, v206, v216
	v_mul_f32_e32 v217, v207, v217
	v_mul_f32_e32 v218, v208, v218
	v_mul_f32_e32 v219, v209, v219
	v_cvt_pk_bf16_f32 v220, v216, v217
	v_cvt_pk_bf16_f32 v221, v218, v219
	s_nop 0
	v_cndmask_b32_e64 v217, v220, v221, s[84:85]
	v_cndmask_b32_e64 v216, v221, v220, s[84:85]
	s_nop 0
	v_mov_b32_dpp v218, v217 quad_perm:[1,0,3,2] row_mask:0xf bank_mask:0xf
	v_perm_b32 v219, v218, v216, v231
	v_perm_b32 v222, v218, v216, v232
	global_store_dword v224, v219, s[78:79] offset:-4096
	global_store_dword v224, v222, s[78:79]
	ds_read_b128 v[108:111], v187
	ds_read_b128 v[112:115], v187 offset:64
	v_mul_f32_e32 v216, 0x3d372713, v210
	v_mul_f32_e32 v217, 0x3d372713, v211
	v_mul_f32_e32 v218, 0x3d372713, v212
	v_mul_f32_e32 v219, 0x3d372713, v213
	v_mul_f32_e32 v216, v210, v216
	v_mul_f32_e32 v217, v211, v217
	v_mul_f32_e32 v218, v212, v218
	v_mul_f32_e32 v219, v213, v219
	v_fma_f32 v216, v210, v216, v210
	v_fma_f32 v217, v211, v217, v211
	v_fma_f32 v218, v212, v218, v212
	v_fma_f32 v219, v213, v219, v213
	v_mul_f32_e32 v216, 0xc0135761, v216
	v_mul_f32_e32 v217, 0xc0135761, v217
	v_mul_f32_e32 v218, 0xc0135761, v218
	v_mul_f32_e32 v219, 0xc0135761, v219
	v_exp_f32_e32 v216, v216
	v_exp_f32_e32 v217, v217
	v_exp_f32_e32 v218, v218
	v_exp_f32_e32 v219, v219
	v_add_f32_e32 v216, 1.0, v216
	v_add_f32_e32 v217, 1.0, v217
	v_add_f32_e32 v218, 1.0, v218
	v_add_f32_e32 v219, 1.0, v219
	v_rcp_f32_e32 v216, v216
	v_rcp_f32_e32 v217, v217
	v_rcp_f32_e32 v218, v218
	v_rcp_f32_e32 v219, v219
	v_mul_f32_e32 v216, v210, v216
	v_mul_f32_e32 v217, v211, v217
	v_mul_f32_e32 v218, v212, v218
	v_mul_f32_e32 v219, v213, v219
	v_cvt_pk_bf16_f32 v220, v216, v217
	v_cvt_pk_bf16_f32 v221, v218, v219
	s_nop 0
	v_cndmask_b32_e64 v217, v220, v221, s[84:85]
	v_cndmask_b32_e64 v216, v221, v220, s[84:85]
	s_nop 0
	v_mov_b32_dpp v218, v217 quad_perm:[1,0,3,2] row_mask:0xf bank_mask:0xf
	v_perm_b32 v219, v218, v216, v231
	v_perm_b32 v222, v218, v216, v232
	global_store_dword v224, v219, s[80:81] offset:-4096
	global_store_dword v224, v222, s[80:81]
	v_add_u32_e32 v224, 0x10000, v224
	s_waitcnt lgkmcnt(0)
	global_load_lds_dwordx4 v[188:189], off
	v_lshl_add_u64 v[188:189], v[188:189], 0, s[76:77]
	s_add_i32 s75, s75, -1
	s_cmp_lg_u32 s75, 0
	s_cbranch_scc1 .Ls5b_step
	s_branch .LBB0_418
